# attention merge hand-packed (pk_mul+pk_fma with op_sel, 8 old-row LDS reads up front), on lean-barrier stack
# speedup vs baseline: 1.0023x; 1.0023x over previous
; __device__ __forceinline__ unsigned cvt_pk_bf16(float lo, float hi) { unsigned r; asm volatile("v_cvt_pk_bf16_f32 %0, %1, %2" : "=v"(r) : "v"(lo), "v"(hi)); return r; }
; #define LAS __attribute__((address_space(3)))
; __device__ __forceinline__ float bf_lo(unsigned w) { return __uint_as_float(w << 16); }
; __device__ __forceinline__ float bf_hi(unsigned w) { return __uint_as_float(w & 0xffff0000u); }
; __device__ __forceinline__ void at_task32(const Args& A, const At32& T, const At32& Tn, bf16x8 (&qf)[4], bf16x8 (&kf)[5][4], LAS unsigned char* lds, LAS unsigned char* vst, int lane) {
;     ...
;     const int ql = qoff + (q32 << dsh);
;     LAS unsigned char* orow = lds + ql * OB_STRIDE + 8 * h;
;     float ca = 0.f, cbb = 1.f, mn = mx, ln = lsum;
;     if (mode != 0) { const f32x2 ml = *(const LAS f32x2*)(ML + 2 * ql); mn = fmaxf(ml[0], mx); ca = __builtin_amdgcn_exp2f(ml[0] - mn); cbb = __builtin_amdgcn_exp2f(mx - mn); ln = ca * ml[1] + cbb * lsum; }
;     if (mode == 2) { const float inv = 1.0f / ln; ca *= inv; cbb *= inv; }
; #pragma unroll
;     for (int db = 0; db < 2; ++db) {
;         u32x2 oldw[4];
; #pragma unroll
;         for (int rg = 0; rg < 4; ++rg) oldw[rg] = mode != 0 ? *(const LAS u32x2*)(orow + (32 * db + 8 * rg) * 2) : (u32x2){0u, 0u};
; #pragma unroll
;         for (int rg = 0; rg < 4; ++rg) { u32x2 w;
;             w.x = cvt_pk_bf16(bf_lo(oldw[rg].x) * ca + o[db][4 * rg] * cbb, bf_hi(oldw[rg].x) * ca + o[db][4 * rg + 1] * cbb);
;             w.y = cvt_pk_bf16(bf_lo(oldw[rg].y) * ca + o[db][4 * rg + 2] * cbb, bf_hi(oldw[rg].y) * ca + o[db][4 * rg + 3] * cbb);
;             *(LAS u32x2*)(orow + (32 * db + 8 * rg) * 2) = w; }
;         asm volatile("" ::: "memory");
;     }
;     if (mode != 2 && h == 0) *(LAS f32x2*)(ML + 2 * ql) = (f32x2){mn, ln};
.LBB0_411:
	s_movk_i32 s2, 0x90
	v_mul_lo_u32 v54, v54, s2
	s_andn2_b64 vcc, exec, s[34:35]
	s_cmp_lg_u32 s11, 2
	v_add_u32_e32 v63, v174, v54
	s_cbranch_vccnz .Lxm_zero
	ds_read_b64 v[212:213], v63
	ds_read_b64 v[214:215], v63 offset:16
	ds_read_b64 v[216:217], v63 offset:32
	ds_read_b64 v[218:219], v63 offset:48
	ds_read_b64 v[220:221], v63 offset:64
	ds_read_b64 v[222:223], v63 offset:80
	ds_read_b64 v[224:225], v63 offset:96
	ds_read_b64 v[226:227], v63 offset:112
	s_branch .Lxm_go
.Lxm_zero:
	v_mov_b32_e32 v212, 0
	v_mov_b32_e32 v213, 0
	v_mov_b32_e32 v214, 0
	v_mov_b32_e32 v215, 0
	v_mov_b32_e32 v216, 0
	v_mov_b32_e32 v217, 0
	v_mov_b32_e32 v218, 0
	v_mov_b32_e32 v219, 0
	v_mov_b32_e32 v220, 0
	v_mov_b32_e32 v221, 0
	v_mov_b32_e32 v222, 0
	v_mov_b32_e32 v223, 0
	v_mov_b32_e32 v224, 0
	v_mov_b32_e32 v225, 0
	v_mov_b32_e32 v226, 0
	v_mov_b32_e32 v227, 0
.Lxm_go:
	s_cselect_b64 s[6:7], -1, 0
	s_and_b64 s[34:35], s[6:7], s[4:5]
	s_waitcnt lgkmcnt(0)
	v_lshlrev_b32_e32 v228, 16, v212
	v_and_b32_e32 v229, 0xffff0000, v212
	v_lshlrev_b32_e32 v230, 16, v213
	v_and_b32_e32 v231, 0xffff0000, v213
	v_pk_mul_f32 v[228:229], v[228:229], v[52:53] op_sel:[0,1] op_sel_hi:[1,1]
	v_pk_mul_f32 v[230:231], v[230:231], v[52:53] op_sel:[0,1] op_sel_hi:[1,1]
	v_pk_fma_f32 v[228:229], v[16:17], v[52:53], v[228:229] op_sel_hi:[1,0,1]
	v_pk_fma_f32 v[230:231], v[18:19], v[52:53], v[230:231] op_sel_hi:[1,0,1]
	v_cvt_pk_bf16_f32 v228, v228, v229
	v_cvt_pk_bf16_f32 v229, v230, v231
	ds_write_b64 v63, v[228:229]
	v_lshlrev_b32_e32 v232, 16, v214
	v_and_b32_e32 v233, 0xffff0000, v214
	v_lshlrev_b32_e32 v234, 16, v215
	v_and_b32_e32 v235, 0xffff0000, v215
	v_pk_mul_f32 v[232:233], v[232:233], v[52:53] op_sel:[0,1] op_sel_hi:[1,1]
	v_pk_mul_f32 v[234:235], v[234:235], v[52:53] op_sel:[0,1] op_sel_hi:[1,1]
	v_pk_fma_f32 v[232:233], v[20:21], v[52:53], v[232:233] op_sel_hi:[1,0,1]
	v_pk_fma_f32 v[234:235], v[22:23], v[52:53], v[234:235] op_sel_hi:[1,0,1]
	v_cvt_pk_bf16_f32 v232, v232, v233
	v_cvt_pk_bf16_f32 v233, v234, v235
	ds_write_b64 v63, v[232:233] offset:16
	v_lshlrev_b32_e32 v228, 16, v216
	v_and_b32_e32 v229, 0xffff0000, v216
	v_lshlrev_b32_e32 v230, 16, v217
	v_and_b32_e32 v231, 0xffff0000, v217
	v_pk_mul_f32 v[228:229], v[228:229], v[52:53] op_sel:[0,1] op_sel_hi:[1,1]
	v_pk_mul_f32 v[230:231], v[230:231], v[52:53] op_sel:[0,1] op_sel_hi:[1,1]
	v_pk_fma_f32 v[228:229], v[24:25], v[52:53], v[228:229] op_sel_hi:[1,0,1]
	v_pk_fma_f32 v[230:231], v[26:27], v[52:53], v[230:231] op_sel_hi:[1,0,1]
	v_cvt_pk_bf16_f32 v228, v228, v229
	v_cvt_pk_bf16_f32 v229, v230, v231
	ds_write_b64 v63, v[228:229] offset:32
	v_lshlrev_b32_e32 v232, 16, v218
	v_and_b32_e32 v233, 0xffff0000, v218
	v_lshlrev_b32_e32 v234, 16, v219
	v_and_b32_e32 v235, 0xffff0000, v219
	v_pk_mul_f32 v[232:233], v[232:233], v[52:53] op_sel:[0,1] op_sel_hi:[1,1]
	v_pk_mul_f32 v[234:235], v[234:235], v[52:53] op_sel:[0,1] op_sel_hi:[1,1]
	v_pk_fma_f32 v[232:233], v[28:29], v[52:53], v[232:233] op_sel_hi:[1,0,1]
	v_pk_fma_f32 v[234:235], v[30:31], v[52:53], v[234:235] op_sel_hi:[1,0,1]
	v_cvt_pk_bf16_f32 v232, v232, v233
	v_cvt_pk_bf16_f32 v233, v234, v235
	ds_write_b64 v63, v[232:233] offset:48
	v_lshlrev_b32_e32 v228, 16, v220
	v_and_b32_e32 v229, 0xffff0000, v220
	v_lshlrev_b32_e32 v230, 16, v221
	v_and_b32_e32 v231, 0xffff0000, v221
	v_pk_mul_f32 v[228:229], v[228:229], v[52:53] op_sel:[0,1] op_sel_hi:[1,1]
	v_pk_mul_f32 v[230:231], v[230:231], v[52:53] op_sel:[0,1] op_sel_hi:[1,1]
	v_pk_fma_f32 v[228:229], v[0:1], v[52:53], v[228:229] op_sel_hi:[1,0,1]
	v_pk_fma_f32 v[230:231], v[2:3], v[52:53], v[230:231] op_sel_hi:[1,0,1]
	v_cvt_pk_bf16_f32 v228, v228, v229
	v_cvt_pk_bf16_f32 v229, v230, v231
	ds_write_b64 v63, v[228:229] offset:64
	v_lshlrev_b32_e32 v232, 16, v222
	v_and_b32_e32 v233, 0xffff0000, v222
	v_lshlrev_b32_e32 v234, 16, v223
	v_and_b32_e32 v235, 0xffff0000, v223
	v_pk_mul_f32 v[232:233], v[232:233], v[52:53] op_sel:[0,1] op_sel_hi:[1,1]
	v_pk_mul_f32 v[234:235], v[234:235], v[52:53] op_sel:[0,1] op_sel_hi:[1,1]
	v_pk_fma_f32 v[232:233], v[4:5], v[52:53], v[232:233] op_sel_hi:[1,0,1]
	v_pk_fma_f32 v[234:235], v[6:7], v[52:53], v[234:235] op_sel_hi:[1,0,1]
	v_cvt_pk_bf16_f32 v232, v232, v233
	v_cvt_pk_bf16_f32 v233, v234, v235
	ds_write_b64 v63, v[232:233] offset:80
	v_lshlrev_b32_e32 v228, 16, v224
	v_and_b32_e32 v229, 0xffff0000, v224
	v_lshlrev_b32_e32 v230, 16, v225
	v_and_b32_e32 v231, 0xffff0000, v225
	v_pk_mul_f32 v[228:229], v[228:229], v[52:53] op_sel:[0,1] op_sel_hi:[1,1]
	v_pk_mul_f32 v[230:231], v[230:231], v[52:53] op_sel:[0,1] op_sel_hi:[1,1]
	v_pk_fma_f32 v[228:229], v[8:9], v[52:53], v[228:229] op_sel_hi:[1,0,1]
	v_pk_fma_f32 v[230:231], v[10:11], v[52:53], v[230:231] op_sel_hi:[1,0,1]
	v_cvt_pk_bf16_f32 v228, v228, v229
	v_cvt_pk_bf16_f32 v229, v230, v231
	ds_write_b64 v63, v[228:229] offset:96
	v_lshlrev_b32_e32 v232, 16, v226
	v_and_b32_e32 v233, 0xffff0000, v226
	v_lshlrev_b32_e32 v234, 16, v227
	v_and_b32_e32 v235, 0xffff0000, v227
	v_pk_mul_f32 v[232:233], v[232:233], v[52:53] op_sel:[0,1] op_sel_hi:[1,1]
	v_pk_mul_f32 v[234:235], v[234:235], v[52:53] op_sel:[0,1] op_sel_hi:[1,1]
	v_pk_fma_f32 v[232:233], v[12:13], v[52:53], v[232:233] op_sel_hi:[1,0,1]
	v_pk_fma_f32 v[234:235], v[14:15], v[52:53], v[234:235] op_sel_hi:[1,0,1]
	v_cvt_pk_bf16_f32 v232, v232, v233
	v_cvt_pk_bf16_f32 v233, v234, v235
	ds_write_b64 v63, v[232:233] offset:112
	s_and_saveexec_b64 s[6:7], s[34:35]
	s_cbranch_execz .LBB0_385
	v_add_u32_e32 v0, 0x12000, v62
	ds_write_b64 v0, v[80:81]
	s_or_b64 exec, exec, s[6:7]
	s_bitcmp0_b32 s30, 0
	s_cbranch_scc0 .LBB0_386
